# P4 out-GEMM epilogue hand-written (batched cross-lane row-sum reduction, batched rows-out)
# speedup vs baseline: 1.0275x; 1.0018x over previous
; DEV u32x2 pk4(f32x4 v) { u32x2 r = {pk_bf16(v[0], v[1]), pk_bf16(v[2], v[3])}; return r; }
;   DEV void operator()(f32x4 (&acc)[2][2][4][2], int brow, int bcol, int wr, int wc, int fr, int fq) const {
;     const int tid = (wr * 4 + wc) * 64 + fq * 16 + fr;
; #pragma unroll
;     for (int ai = 0; ai < 2; ++ai)
; #pragma unroll
;       for (int m = 0; m < 4; ++m) {
;         const int rl = ai * 128 + wr * 64 + m * 16 + fr, tok = brow + rl;
;         float ss = 0.f;
; #pragma unroll
;         for (int bj = 0; bj < 2; ++bj)
; #pragma unroll
;           for (int n = 0; n < 2; ++n) {
;             const int cl = bj * 128 + wc * 32 + n * 16 + fq * 4;
;             const f32x4 v = acc[ai][bj][m][n];
;             tile_put4(rl, cl, pk4(v));
;             ss += v[0] * v[0] + v[1] * v[1] + v[2] * v[2] + v[3] * v[3];
;           }
;         ss += __shfl_xor(ss, 16); ss += __shfl_xor(ss, 32);
;         if (fq == 0) part[(size_t)((bcol >> 8) * 4 + wc) * NTOK + tok] = ss;
.LBB0_2165:
	s_or_b64 exec, exec, s[4:5]
	v_and_b32_e32 v133, 15, v141
	v_bfe_u32 v134, v141, 4, 2
	v_bfe_u32 v135, v141, 6, 2
	v_lshrrev_b32_e32 v136, 8, v141
	v_lshl_add_u32 v137, v136, 6, v133
	v_lshlrev_b32_e32 v137, 9, v137
	v_and_b32_e32 v138, 1, v134
	v_lshl_add_u32 v137, v138, 3, v137
	v_lshrrev_b32_e32 v138, 1, v134
	v_lshl_add_u32 v138, v135, 2, v138
	v_xor_b32_e32 v138, v138, v133
	v_lshl_add_u32 v142, v138, 4, v137
	v_xor_b32_e32 v138, 2, v138
	v_lshl_add_u32 v143, v138, 4, v137
	v_add_u32_e32 v144, 0x10000, v142
	v_add_u32_e32 v145, 0x10000, v143
	v_xor_b32_e32 v130, 16, v219
	v_lshlrev_b32_e32 v130, 2, v130
	v_xor_b32_e32 v131, 32, v219
	v_lshlrev_b32_e32 v131, 2, v131
	v_mov_b32_e32 v132, 64
	s_lshl_b32 s10, s21, 2
	v_add_u32_e32 v146, s10, v135
	v_lshlrev_b32_e32 v146, 13, v146
	s_lshl_b32 s10, s8, 8
	v_add_u32_e32 v146, s10, v146
	v_lshl_add_u32 v146, v136, 6, v146
	v_add_lshl_u32 v146, v146, v133, 2
	v_mul_f32_e32 v156, v125, v125
	v_fmac_f32_e32 v156, v124, v124
	v_fmac_f32_e32 v156, v126, v126
	v_fmac_f32_e32 v156, v127, v127
	v_cvt_pk_bf16_f32 v124, v124, v125
	v_cvt_pk_bf16_f32 v125, v126, v127
	ds_write_b64 v142, v[124:125]
	v_mul_f32_e32 v157, v117, v117
	v_fmac_f32_e32 v157, v116, v116
	v_fmac_f32_e32 v157, v118, v118
	v_fmac_f32_e32 v157, v119, v119
	v_cvt_pk_bf16_f32 v116, v116, v117
	v_cvt_pk_bf16_f32 v117, v118, v119
	ds_write_b64 v143, v[116:117]
	v_mul_f32_e32 v158, v121, v121
	v_fmac_f32_e32 v158, v120, v120
	v_fmac_f32_e32 v158, v122, v122
	v_fmac_f32_e32 v158, v123, v123
	v_cvt_pk_bf16_f32 v120, v120, v121
	v_cvt_pk_bf16_f32 v121, v122, v123
	ds_write_b64 v142, v[120:121] offset:256
	v_mul_f32_e32 v159, v113, v113
	v_fmac_f32_e32 v159, v112, v112
	v_fmac_f32_e32 v159, v114, v114
	v_fmac_f32_e32 v159, v115, v115
	v_cvt_pk_bf16_f32 v112, v112, v113
	v_cvt_pk_bf16_f32 v113, v114, v115
	ds_write_b64 v143, v[112:113] offset:256
	v_add_f32_e32 v148, v156, v157
	v_add_f32_e32 v148, v148, v158
	v_add_f32_e32 v148, v148, v159
	v_mul_f32_e32 v156, v109, v109
	v_fmac_f32_e32 v156, v108, v108
	v_fmac_f32_e32 v156, v110, v110
	v_fmac_f32_e32 v156, v111, v111
	v_cvt_pk_bf16_f32 v108, v108, v109
	v_cvt_pk_bf16_f32 v109, v110, v111
	ds_write_b64 v142, v[108:109] offset:8448
	v_mul_f32_e32 v157, v101, v101
	v_fmac_f32_e32 v157, v100, v100
	v_fmac_f32_e32 v157, v102, v102
	v_fmac_f32_e32 v157, v103, v103
	v_cvt_pk_bf16_f32 v100, v100, v101
	v_cvt_pk_bf16_f32 v101, v102, v103
	ds_write_b64 v143, v[100:101] offset:8448
	v_mul_f32_e32 v158, v105, v105
	v_fmac_f32_e32 v158, v104, v104
	v_fmac_f32_e32 v158, v106, v106
	v_fmac_f32_e32 v158, v107, v107
	v_cvt_pk_bf16_f32 v104, v104, v105
	v_cvt_pk_bf16_f32 v105, v106, v107
	ds_write_b64 v142, v[104:105] offset:8192
	v_mul_f32_e32 v159, v97, v97
	v_fmac_f32_e32 v159, v96, v96
	v_fmac_f32_e32 v159, v98, v98
	v_fmac_f32_e32 v159, v99, v99
	v_cvt_pk_bf16_f32 v96, v96, v97
	v_cvt_pk_bf16_f32 v97, v98, v99
	ds_write_b64 v143, v[96:97] offset:8192
	v_add_f32_e32 v149, v156, v157
	v_add_f32_e32 v149, v149, v158
	v_add_f32_e32 v149, v149, v159
	v_mul_f32_e32 v156, v93, v93
	v_fmac_f32_e32 v156, v92, v92
	v_fmac_f32_e32 v156, v94, v94
	v_fmac_f32_e32 v156, v95, v95
	v_cvt_pk_bf16_f32 v92, v92, v93
	v_cvt_pk_bf16_f32 v93, v94, v95
	ds_write_b64 v142, v[92:93] offset:16384
	v_mul_f32_e32 v157, v89, v89
	v_fmac_f32_e32 v157, v88, v88
	v_fmac_f32_e32 v157, v90, v90
	v_fmac_f32_e32 v157, v91, v91
	v_cvt_pk_bf16_f32 v88, v88, v89
	v_cvt_pk_bf16_f32 v89, v90, v91
	ds_write_b64 v143, v[88:89] offset:16384
	v_mul_f32_e32 v158, v85, v85
	v_fmac_f32_e32 v158, v84, v84
	v_fmac_f32_e32 v158, v86, v86
	v_fmac_f32_e32 v158, v87, v87
	v_cvt_pk_bf16_f32 v84, v84, v85
	v_cvt_pk_bf16_f32 v85, v86, v87
	ds_write_b64 v142, v[84:85] offset:16640
	v_mul_f32_e32 v159, v81, v81
	v_fmac_f32_e32 v159, v80, v80
	v_fmac_f32_e32 v159, v82, v82
	v_fmac_f32_e32 v159, v83, v83
	v_cvt_pk_bf16_f32 v80, v80, v81
	v_cvt_pk_bf16_f32 v81, v82, v83
	ds_write_b64 v143, v[80:81] offset:16640
	v_add_f32_e32 v150, v156, v157
	v_add_f32_e32 v150, v150, v158
	v_add_f32_e32 v150, v150, v159
	v_mul_f32_e32 v156, v77, v77
	v_fmac_f32_e32 v156, v76, v76
	v_fmac_f32_e32 v156, v78, v78
	v_fmac_f32_e32 v156, v79, v79
	v_cvt_pk_bf16_f32 v76, v76, v77
	v_cvt_pk_bf16_f32 v77, v78, v79
	ds_write_b64 v142, v[76:77] offset:24832
	v_mul_f32_e32 v157, v73, v73
	v_fmac_f32_e32 v157, v72, v72
	v_fmac_f32_e32 v157, v74, v74
	v_fmac_f32_e32 v157, v75, v75
	v_cvt_pk_bf16_f32 v72, v72, v73
	v_cvt_pk_bf16_f32 v73, v74, v75
	ds_write_b64 v143, v[72:73] offset:24832
	v_mul_f32_e32 v158, v69, v69
	v_fmac_f32_e32 v158, v68, v68
	v_fmac_f32_e32 v158, v70, v70
	v_fmac_f32_e32 v158, v71, v71
	v_cvt_pk_bf16_f32 v68, v68, v69
	v_cvt_pk_bf16_f32 v69, v70, v71
	ds_write_b64 v142, v[68:69] offset:24576
	v_mul_f32_e32 v159, v65, v65
	v_fmac_f32_e32 v159, v64, v64
	v_fmac_f32_e32 v159, v66, v66
	v_fmac_f32_e32 v159, v67, v67
	v_cvt_pk_bf16_f32 v64, v64, v65
	v_cvt_pk_bf16_f32 v65, v66, v67
	ds_write_b64 v143, v[64:65] offset:24576
	v_add_f32_e32 v151, v156, v157
	v_add_f32_e32 v151, v151, v158
	v_add_f32_e32 v151, v151, v159
	v_mul_f32_e32 v156, v61, v61
	v_fmac_f32_e32 v156, v60, v60
	v_fmac_f32_e32 v156, v62, v62
	v_fmac_f32_e32 v156, v63, v63
	v_cvt_pk_bf16_f32 v60, v60, v61
	v_cvt_pk_bf16_f32 v61, v62, v63
	ds_write_b64 v144, v[60:61]
	v_mul_f32_e32 v157, v57, v57
	v_fmac_f32_e32 v157, v56, v56
	v_fmac_f32_e32 v157, v58, v58
	v_fmac_f32_e32 v157, v59, v59
	v_cvt_pk_bf16_f32 v56, v56, v57
	v_cvt_pk_bf16_f32 v57, v58, v59
	ds_write_b64 v145, v[56:57]
	v_mul_f32_e32 v158, v53, v53
	v_fmac_f32_e32 v158, v52, v52
	v_fmac_f32_e32 v158, v54, v54
	v_fmac_f32_e32 v158, v55, v55
; DEV u32x2 pk4(f32x4 v) { u32x2 r = {pk_bf16(v[0], v[1]), pk_bf16(v[2], v[3])}; return r; }
;   DEV void operator()(f32x4 (&acc)[2][2][4][2], int brow, int bcol, int wr, int wc, int fr, int fq) const {
;     ...
;           for (int n = 0; n < 2; ++n) {
;             const int cl = bj * 128 + wc * 32 + n * 16 + fq * 4;
;             const f32x4 v = acc[ai][bj][m][n];
;             tile_put4(rl, cl, pk4(v));
;             ss += v[0] * v[0] + v[1] * v[1] + v[2] * v[2] + v[3] * v[3];
;           }
;         ss += __shfl_xor(ss, 16); ss += __shfl_xor(ss, 32);
;         if (fq == 0) part[(size_t)((bcol >> 8) * 4 + wc) * NTOK + tok] = ss;
;       }
;     __syncthreads();
;     tile_rows_out(y + (size_t)brow * 2048 + bcol, 2048, tid);
	v_cvt_pk_bf16_f32 v52, v52, v53
	v_cvt_pk_bf16_f32 v53, v54, v55
	ds_write_b64 v144, v[52:53] offset:256
	v_mul_f32_e32 v159, v49, v49
	v_fmac_f32_e32 v159, v48, v48
	v_fmac_f32_e32 v159, v50, v50
	v_fmac_f32_e32 v159, v51, v51
	v_cvt_pk_bf16_f32 v48, v48, v49
	v_cvt_pk_bf16_f32 v49, v50, v51
	ds_write_b64 v145, v[48:49] offset:256
	v_add_f32_e32 v152, v156, v157
	v_add_f32_e32 v152, v152, v158
	v_add_f32_e32 v152, v152, v159
	v_mul_f32_e32 v156, v45, v45
	v_fmac_f32_e32 v156, v44, v44
	v_fmac_f32_e32 v156, v46, v46
	v_fmac_f32_e32 v156, v47, v47
	v_cvt_pk_bf16_f32 v44, v44, v45
	v_cvt_pk_bf16_f32 v45, v46, v47
	ds_write_b64 v144, v[44:45] offset:8448
	v_mul_f32_e32 v157, v41, v41
	v_fmac_f32_e32 v157, v40, v40
	v_fmac_f32_e32 v157, v42, v42
	v_fmac_f32_e32 v157, v43, v43
	v_cvt_pk_bf16_f32 v40, v40, v41
	v_cvt_pk_bf16_f32 v41, v42, v43
	ds_write_b64 v145, v[40:41] offset:8448
	v_mul_f32_e32 v158, v37, v37
	v_fmac_f32_e32 v158, v36, v36
	v_fmac_f32_e32 v158, v38, v38
	v_fmac_f32_e32 v158, v39, v39
	v_cvt_pk_bf16_f32 v36, v36, v37
	v_cvt_pk_bf16_f32 v37, v38, v39
	ds_write_b64 v144, v[36:37] offset:8192
	v_mul_f32_e32 v159, v33, v33
	v_fmac_f32_e32 v159, v32, v32
	v_fmac_f32_e32 v159, v34, v34
	v_fmac_f32_e32 v159, v35, v35
	v_cvt_pk_bf16_f32 v32, v32, v33
	v_cvt_pk_bf16_f32 v33, v34, v35
	ds_write_b64 v145, v[32:33] offset:8192
	v_add_f32_e32 v153, v156, v157
	v_add_f32_e32 v153, v153, v158
	v_add_f32_e32 v153, v153, v159
	v_mul_f32_e32 v156, v29, v29
	v_fmac_f32_e32 v156, v28, v28
	v_fmac_f32_e32 v156, v30, v30
	v_fmac_f32_e32 v156, v31, v31
	v_cvt_pk_bf16_f32 v28, v28, v29
	v_cvt_pk_bf16_f32 v29, v30, v31
	ds_write_b64 v144, v[28:29] offset:16384
	v_mul_f32_e32 v157, v25, v25
	v_fmac_f32_e32 v157, v24, v24
	v_fmac_f32_e32 v157, v26, v26
	v_fmac_f32_e32 v157, v27, v27
	v_cvt_pk_bf16_f32 v24, v24, v25
	v_cvt_pk_bf16_f32 v25, v26, v27
	ds_write_b64 v145, v[24:25] offset:16384
	v_mul_f32_e32 v158, v21, v21
	v_fmac_f32_e32 v158, v20, v20
	v_fmac_f32_e32 v158, v22, v22
	v_fmac_f32_e32 v158, v23, v23
	v_cvt_pk_bf16_f32 v20, v20, v21
	v_cvt_pk_bf16_f32 v21, v22, v23
	ds_write_b64 v144, v[20:21] offset:16640
	v_mul_f32_e32 v159, v17, v17
	v_fmac_f32_e32 v159, v16, v16
	v_fmac_f32_e32 v159, v18, v18
	v_fmac_f32_e32 v159, v19, v19
	v_cvt_pk_bf16_f32 v16, v16, v17
	v_cvt_pk_bf16_f32 v17, v18, v19
	ds_write_b64 v145, v[16:17] offset:16640
	v_add_f32_e32 v154, v156, v157
	v_add_f32_e32 v154, v154, v158
	v_add_f32_e32 v154, v154, v159
	v_mul_f32_e32 v156, v13, v13
	v_fmac_f32_e32 v156, v12, v12
	v_fmac_f32_e32 v156, v14, v14
	v_fmac_f32_e32 v156, v15, v15
	v_cvt_pk_bf16_f32 v12, v12, v13
	v_cvt_pk_bf16_f32 v13, v14, v15
	ds_write_b64 v144, v[12:13] offset:24832
	v_mul_f32_e32 v157, v9, v9
	v_fmac_f32_e32 v157, v8, v8
	v_fmac_f32_e32 v157, v10, v10
	v_fmac_f32_e32 v157, v11, v11
	v_cvt_pk_bf16_f32 v8, v8, v9
	v_cvt_pk_bf16_f32 v9, v10, v11
	ds_write_b64 v145, v[8:9] offset:24832
	v_mul_f32_e32 v158, v5, v5
	v_fmac_f32_e32 v158, v4, v4
	v_fmac_f32_e32 v158, v6, v6
	v_fmac_f32_e32 v158, v7, v7
	v_cvt_pk_bf16_f32 v4, v4, v5
	v_cvt_pk_bf16_f32 v5, v6, v7
	ds_write_b64 v144, v[4:5] offset:24576
	v_mul_f32_e32 v159, v1, v1
	v_fmac_f32_e32 v159, v0, v0
	v_fmac_f32_e32 v159, v2, v2
	v_fmac_f32_e32 v159, v3, v3
	v_cvt_pk_bf16_f32 v0, v0, v1
	v_cvt_pk_bf16_f32 v1, v2, v3
	ds_write_b64 v145, v[0:1] offset:24576
	v_add_f32_e32 v155, v156, v157
	v_add_f32_e32 v155, v155, v158
	v_add_f32_e32 v155, v155, v159
	ds_bpermute_b32 v164, v130, v148
	ds_bpermute_b32 v165, v130, v149
	ds_bpermute_b32 v166, v130, v150
	ds_bpermute_b32 v167, v130, v151
	ds_bpermute_b32 v168, v130, v152
	ds_bpermute_b32 v169, v130, v153
	ds_bpermute_b32 v170, v130, v154
	ds_bpermute_b32 v171, v130, v155
	s_waitcnt lgkmcnt(0)
	v_add_f32_e32 v148, v148, v164
	v_add_f32_e32 v149, v149, v165
	v_add_f32_e32 v150, v150, v166
	v_add_f32_e32 v151, v151, v167
	v_add_f32_e32 v152, v152, v168
	v_add_f32_e32 v153, v153, v169
	v_add_f32_e32 v154, v154, v170
	v_add_f32_e32 v155, v155, v171
	ds_bpermute_b32 v164, v131, v148
	ds_bpermute_b32 v165, v131, v149
	ds_bpermute_b32 v166, v131, v150
	ds_bpermute_b32 v167, v131, v151
	ds_bpermute_b32 v168, v131, v152
	ds_bpermute_b32 v169, v131, v153
	ds_bpermute_b32 v170, v131, v154
	ds_bpermute_b32 v171, v131, v155
	s_waitcnt lgkmcnt(0)
	v_add_f32_e32 v148, v148, v164
	v_add_f32_e32 v149, v149, v165
	v_add_f32_e32 v150, v150, v166
	v_add_f32_e32 v151, v151, v167
	v_add_f32_e32 v152, v152, v168
	v_add_f32_e32 v153, v153, v169
	v_add_f32_e32 v154, v154, v170
	v_add_f32_e32 v155, v155, v171
	v_readlane_b32 s10, v253, 2
	v_readlane_b32 s11, v253, 3
	v_cmp_eq_u32_e32 vcc, 0, v134
	s_nop 4
	s_and_saveexec_b64 s[4:5], vcc
	global_store_dword v146, v148, s[10:11] sc1
	global_store_dword v146, v149, s[10:11] offset:64 sc1
	global_store_dword v146, v150, s[10:11] offset:128 sc1
	global_store_dword v146, v151, s[10:11] offset:192 sc1
	global_store_dword v146, v152, s[10:11] offset:512 sc1
	global_store_dword v146, v153, s[10:11] offset:576 sc1
	global_store_dword v146, v154, s[10:11] offset:640 sc1
	global_store_dword v146, v155, s[10:11] offset:704 sc1
	s_or_b64 exec, exec, s[4:5]
	v_readlane_b32 s12, v253, 0
	v_readlane_b32 s13, v253, 1
	s_lshl_b32 s10, s8, 19
	s_lshl_b32 s11, s21, 8
	s_add_i32 s10, s10, s11
	s_lshl_b32 s10, s10, 1
	s_add_u32 s12, s12, s10
	s_addc_u32 s13, s13, 0
	v_lshrrev_b32_e32 v160, 5, v141
	v_and_b32_e32 v161, 31, v141
	v_xor_b32_e32 v161, v161, v160
	v_lshlrev_b32_e32 v162, 12, v160
	v_mov_b32_e32 v163, v162
	v_lshl_add_u32 v162, v161, 4, v162
	v_xor_b32_e32 v161, 16, v161
	v_lshl_add_u32 v163, v161, 4, v163
	v_add_u32_e32 v163, 0x10000, v163
	v_lshlrev_b32_e32 v172, 4, v141
	v_add_u32_e32 v173, 0x10000, v172
	s_waitcnt lgkmcnt(0)
	s_barrier
; template <bool NT = false>
; DEV void tile_rows_out(bf16_t* __restrict__ out0, const size_t ld, const int tid) {
; #pragma unroll
;   for (int i = 0; i < 16; ++i) {
;     const int id = i * 512 + tid, r = id >> 5, pos = id & 31, c = pos ^ (r & 31);
;     const u32x4 v = *(const u32x4*)(smem + r * 512 + pos * 16);
;     if (NT) __builtin_nontemporal_store(v, (u32x4*)(out0 + (size_t)r * ld + 8 * c)); else *(u32x4*)(out0 + (size_t)r * ld + 8 * c) = v;
;   }
; DEV void panel_publish(unsigned* cnt, const int tidx) {
;   asm volatile("s_waitcnt vmcnt(0)" ::: "memory");
;   __syncthreads();
;   if (tidx == 0) {
;     __builtin_amdgcn_fence(__ATOMIC_RELEASE, "agent");
;     asm volatile("s_waitcnt vmcnt(0)" ::: "memory");
;     __hip_atomic_fetch_add(cnt, 1u, __ATOMIC_RELAXED, __HIP_MEMORY_SCOPE_AGENT);
;   }
	ds_read_b128 v[0:3], v172
	ds_read_b128 v[4:7], v172 offset:8192
	ds_read_b128 v[8:11], v172 offset:16384
	ds_read_b128 v[12:15], v172 offset:24576
	ds_read_b128 v[16:19], v172 offset:32768
	ds_read_b128 v[20:23], v172 offset:40960
	ds_read_b128 v[24:27], v172 offset:49152
	ds_read_b128 v[28:31], v172 offset:57344
	ds_read_b128 v[32:35], v173
	ds_read_b128 v[36:39], v173 offset:8192
	ds_read_b128 v[40:43], v173 offset:16384
	ds_read_b128 v[44:47], v173 offset:24576
	ds_read_b128 v[48:51], v173 offset:32768
	ds_read_b128 v[52:55], v173 offset:40960
	ds_read_b128 v[56:59], v173 offset:49152
	ds_read_b128 v[60:63], v173 offset:57344
	s_waitcnt lgkmcnt(15)
	global_store_dwordx4 v162, v[0:3], s[12:13] sc1
	v_add_u32_e32 v162, 0x20000, v162
	s_waitcnt lgkmcnt(14)
	global_store_dwordx4 v163, v[4:7], s[12:13] sc1
	v_add_u32_e32 v163, 0x20000, v163
	s_waitcnt lgkmcnt(13)
	global_store_dwordx4 v162, v[8:11], s[12:13] sc1
	v_add_u32_e32 v162, 0x20000, v162
	s_waitcnt lgkmcnt(12)
	global_store_dwordx4 v163, v[12:15], s[12:13] sc1
	v_add_u32_e32 v163, 0x20000, v163
	s_waitcnt lgkmcnt(11)
	global_store_dwordx4 v162, v[16:19], s[12:13] sc1
	v_add_u32_e32 v162, 0x20000, v162
	s_waitcnt lgkmcnt(10)
	global_store_dwordx4 v163, v[20:23], s[12:13] sc1
	v_add_u32_e32 v163, 0x20000, v163
	s_waitcnt lgkmcnt(9)
	global_store_dwordx4 v162, v[24:27], s[12:13] sc1
	v_add_u32_e32 v162, 0x20000, v162
	s_waitcnt lgkmcnt(8)
	global_store_dwordx4 v163, v[28:31], s[12:13] sc1
	v_add_u32_e32 v163, 0x20000, v163
	s_waitcnt lgkmcnt(7)
	global_store_dwordx4 v162, v[32:35], s[12:13] sc1
	v_add_u32_e32 v162, 0x20000, v162
	s_waitcnt lgkmcnt(6)
	global_store_dwordx4 v163, v[36:39], s[12:13] sc1
	v_add_u32_e32 v163, 0x20000, v163
	s_waitcnt lgkmcnt(5)
	global_store_dwordx4 v162, v[40:43], s[12:13] sc1
	v_add_u32_e32 v162, 0x20000, v162
	s_waitcnt lgkmcnt(4)
	global_store_dwordx4 v163, v[44:47], s[12:13] sc1
	v_add_u32_e32 v163, 0x20000, v163
	s_waitcnt lgkmcnt(3)
	global_store_dwordx4 v162, v[48:51], s[12:13] sc1
	v_add_u32_e32 v162, 0x20000, v162
	s_waitcnt lgkmcnt(2)
	global_store_dwordx4 v163, v[52:55], s[12:13] sc1
	v_add_u32_e32 v163, 0x20000, v163
	s_waitcnt lgkmcnt(1)
	global_store_dwordx4 v162, v[56:59], s[12:13] sc1
	s_waitcnt lgkmcnt(0)
	global_store_dwordx4 v163, v[60:63], s[12:13] sc1
	s_branch .Lp4_join
.Lp4_join:
	s_waitcnt vmcnt(0)
	s_barrier
	s_and_saveexec_b64 s[4:5], s[0:1]
	s_cbranch_execz .LBB0_2189
	s_mov_b64 s[10:11], exec
	s_lshl_b64 s[0:1], s[8:9], 2
	v_readlane_b32 s7, v254, 4
	s_waitcnt vmcnt(0)
	s_waitcnt vmcnt(0)
	v_mbcnt_lo_u32_b32 v0, s10, 0
	s_add_u32 s0, s7, s0
	v_readlane_b32 s7, v254, 5
	v_mbcnt_hi_u32_b32 v0, s11, v0
	s_addc_u32 s1, s7, s1
	v_cmp_eq_u32_e32 vcc, 0, v0
	s_and_saveexec_b64 s[8:9], vcc
	s_cbranch_execz .LBB0_2186
	s_bcnt1_i32_b64 s7, s[10:11]
	v_mov_b32_e32 v0, s7
	global_atomic_add v177, v0, s[0:1]
